# trimmed attention plus next-unit prefetch (Q fragments and first three tiles requested before the current unit is written out)
# baseline (speedup 1.0000x reference)
.Lat2_noprio:
	v_and_b32_e32 v228, 31, v246
	v_lshrrev_b32_e32 v229, 5, v246
	v_lshlrev_b32_e32 v200, 10, v246
	s_lshl_b32 s4, s27, 4
	v_add_u32_e32 v200, s4, v200
	v_lshrrev_b32_e32 v230, 2, v246
	s_and_b32 s4, s27, 3
	s_lshl_b32 s4, s4, 4
	v_add_u32_e32 v230, s4, v230
	v_lshlrev_b32_e32 v230, 10, v230
	v_and_b32_e32 v231, 3, v246
	v_lshlrev_b32_e32 v231, 4, v231
	s_lshr_b32 s4, s27, 2
	s_lshl_b32 s4, s4, 6
	v_add3_u32 v201, v230, v231, s4
	v_add_u32_e32 v202, 0x80, v201
	s_lshl_b32 s4, s27, 5
	v_add_u32_e32 v230, s4, v228
	v_lshlrev_b32_e32 v225, 10, v230
	v_lshl_add_u32 v225, v229, 4, v225
	v_lshlrev_b32_e32 v231, 2, v229
	v_sub_u32_e32 v218, v230, v231
	v_lshlrev_b32_e32 v203, 10, v229
	v_lshl_add_u32 v203, v228, 4, v203
	v_bfe_u32 v230, v246, 4, 1
	v_lshlrev_b32_e32 v230, 5, v230
	v_and_b32_e32 v231, 3, v246
	v_lshl_add_u32 v230, v231, 3, v230
	v_bfe_u32 v231, v246, 2, 2
	v_lshl_add_u32 v231, v229, 2, v231
	v_lshl_add_u32 v230, v231, 6, v230
	v_add_u32_e32 v204, 0x8000, v230
	s_lshl_b32 s4, s27, 8
	s_add_i32 s4, s4, 0x18000
	v_lshl_add_u32 v220, v228, 2, s4
	v_lshl_add_u32 v221, v229, 4, s4
	s_lshl_b32 s4, s27, 11
	s_add_i32 s4, s4, 0x18800
	v_lshlrev_b32_e32 v230, 8, v229
	v_lshl_add_u32 v230, v228, 1, v230
	v_add_u32_e32 v222, s4, v230
	v_lshrrev_b32_e32 v230, 2, v246
	v_and_b32_e32 v231, 3, v246
	v_lshlrev_b32_e32 v223, 6, v230
	v_lshl_add_u32 v223, v231, 4, v223
	v_add_u32_e32 v223, s4, v223
	s_lshl_b32 s4, s27, 5
	v_add_u32_e32 v230, s4, v230
	v_lshlrev_b32_e32 v224, 11, v230
	v_lshl_add_u32 v224, v231, 4, v224
	v_mov_b32_e32 v219, 0xff800000
	s_mov_b32 s26, 0
	s_and_b32 s4, s38, 3
	s_lshl_b32 s4, s4, 1
	s_lshr_b32 s5, s26, 1
	s_add_i32 s4, s4, s5
	s_sub_i32 s5, 15, s4
	s_bitcmp1_b32 s26, 0
	s_cselect_b32 s4, s4, s5
	s_lshl_b32 s39, s4, 2
	s_add_i32 s39, s39, 4
	s_sub_i32 s18, s39, 4
	s_lshr_b32 s5, s38, 5
	s_lshl_b32 s5, s5, 12
	s_lshl_b32 s6, s4, 8
	s_add_i32 s6, s6, s5
	s_bfe_u32 s7, s38, 0x30002
	s_lshl_b32 s14, s6, 10
	s_lshl_b32 s15, s7, 7
	s_add_i32 s14, s14, s15
	s_add_u32 s72, s54, s14
	s_addc_u32 s73, s55, 0
	s_lshl_b32 s14, s5, 10
	s_add_i32 s15, s14, s15
	s_add_i32 s15, s15, 0x2000000
	s_add_u32 s74, s54, s15
	s_addc_u32 s75, s55, 0
	s_lshr_b32 s15, s7, 1
	s_lshl_b32 s15, s15, 8
	s_add_i32 s14, s14, s15
	s_add_u32 s76, s64, s14
	s_addc_u32 s77, s65, 0
	s_lshl_b32 s14, s6, 11
	s_lshl_b32 s15, s7, 8
	s_add_i32 s14, s14, s15
	s_add_u32 s78, s50, s14
	s_addc_u32 s79, s51, 0
	global_load_dwordx4 v[148:151], v225, s[72:73] offset:0
	global_load_dwordx4 v[152:155], v225, s[72:73] offset:32
	global_load_dwordx4 v[156:159], v225, s[72:73] offset:64
	global_load_dwordx4 v[160:163], v225, s[72:73] offset:96
	s_mov_b64 s[80:81], s[74:75]
	s_mov_b64 s[82:83], s[76:77]
	s_mov_b32 s59, 0
	s_mov_b32 s60, 0x2000
	s_mov_b32 s61, 0x4000
	s_mov_b32 s25, 0x6000
	s_add_i32 m0, s59, s16
	s_lshl_b32 s5, s59, 1
	global_load_lds_dwordx4 v200, s[80:81]
	s_add_i32 m0, s5, s8
	s_add_u32 s80, s80, 0x10000
	s_addc_u32 s81, s81, 0
	global_load_lds_dwordx4 v201, s[82:83]
	s_add_i32 m0, m0, 0x2000
	s_nop 0
	global_load_lds_dwordx4 v202, s[82:83]
	s_add_u32 s82, s82, 0x10000
	s_addc_u32 s83, s83, 0
	s_add_i32 m0, s60, s16
	s_lshl_b32 s5, s60, 1
	global_load_lds_dwordx4 v200, s[80:81]
	s_add_i32 m0, s5, s8
	s_add_u32 s80, s80, 0x10000
	s_addc_u32 s81, s81, 0
	global_load_lds_dwordx4 v201, s[82:83]
	s_add_i32 m0, m0, 0x2000
	s_nop 0
	global_load_lds_dwordx4 v202, s[82:83]
	s_add_u32 s82, s82, 0x10000
	s_addc_u32 s83, s83, 0
	s_add_i32 m0, s61, s16
	s_lshl_b32 s5, s61, 1
	global_load_lds_dwordx4 v200, s[80:81]
	s_add_i32 m0, s5, s8
	s_add_u32 s80, s80, 0x10000
	s_addc_u32 s81, s81, 0
	global_load_lds_dwordx4 v201, s[82:83]
	s_add_i32 m0, m0, 0x2000
	s_nop 0
	global_load_lds_dwordx4 v202, s[82:83]
	s_add_u32 s82, s82, 0x10000
	s_addc_u32 s83, s83, 0

.Lat2_skip_25:
	s_mov_b64 s[0:1], s[78:79]
	s_add_i32 s26, s26, 1
	s_cmp_lt_u32 s26, 4
	s_cbranch_scc0 .Lat2_nopf_29
	s_and_b32 s4, s38, 3
	s_lshl_b32 s4, s4, 1
	s_lshr_b32 s5, s26, 1
	s_add_i32 s4, s4, s5
	s_sub_i32 s5, 15, s4
	s_bitcmp1_b32 s26, 0
	s_cselect_b32 s4, s4, s5
	s_lshl_b32 s39, s4, 2
	s_add_i32 s39, s39, 4
	s_sub_i32 s18, s39, 4
	s_lshr_b32 s5, s38, 5
	s_lshl_b32 s5, s5, 12
	s_lshl_b32 s6, s4, 8
	s_add_i32 s6, s6, s5
	s_bfe_u32 s7, s38, 0x30002
	s_lshl_b32 s14, s6, 10
	s_lshl_b32 s15, s7, 7
	s_add_i32 s14, s14, s15
	s_add_u32 s72, s54, s14
	s_addc_u32 s73, s55, 0
	s_lshl_b32 s14, s5, 10
	s_add_i32 s15, s14, s15
	s_add_i32 s15, s15, 0x2000000
	s_add_u32 s74, s54, s15
	s_addc_u32 s75, s55, 0
	s_lshr_b32 s15, s7, 1
	s_lshl_b32 s15, s15, 8
	s_add_i32 s14, s14, s15
	s_add_u32 s76, s64, s14
	s_addc_u32 s77, s65, 0
	s_lshl_b32 s14, s6, 11
	s_lshl_b32 s15, s7, 8
	s_add_i32 s14, s14, s15
	s_add_u32 s78, s50, s14
	s_addc_u32 s79, s51, 0
	global_load_dwordx4 v[148:151], v225, s[72:73] offset:0
	global_load_dwordx4 v[152:155], v225, s[72:73] offset:32
	global_load_dwordx4 v[156:159], v225, s[72:73] offset:64
	global_load_dwordx4 v[160:163], v225, s[72:73] offset:96
	s_mov_b64 s[80:81], s[74:75]
	s_mov_b64 s[82:83], s[76:77]
	s_mov_b32 s59, 0
	s_mov_b32 s60, 0x2000
	s_mov_b32 s61, 0x4000
	s_mov_b32 s25, 0x6000
	s_add_i32 m0, s59, s16
	s_lshl_b32 s5, s59, 1
	global_load_lds_dwordx4 v200, s[80:81]
	s_add_i32 m0, s5, s8
	s_add_u32 s80, s80, 0x10000
	s_addc_u32 s81, s81, 0
	global_load_lds_dwordx4 v201, s[82:83]
	s_add_i32 m0, m0, 0x2000
	s_nop 0
	global_load_lds_dwordx4 v202, s[82:83]
	s_add_u32 s82, s82, 0x10000
	s_addc_u32 s83, s83, 0
	s_add_i32 m0, s60, s16
	s_lshl_b32 s5, s60, 1
	global_load_lds_dwordx4 v200, s[80:81]
	s_add_i32 m0, s5, s8
	s_add_u32 s80, s80, 0x10000
	s_addc_u32 s81, s81, 0
	global_load_lds_dwordx4 v201, s[82:83]
	s_add_i32 m0, m0, 0x2000
	s_nop 0
	global_load_lds_dwordx4 v202, s[82:83]
	s_add_u32 s82, s82, 0x10000
	s_addc_u32 s83, s83, 0
	s_add_i32 m0, s61, s16
	s_lshl_b32 s5, s61, 1
	global_load_lds_dwordx4 v200, s[80:81]
	s_add_i32 m0, s5, s8
	s_add_u32 s80, s80, 0x10000
	s_addc_u32 s81, s81, 0
	global_load_lds_dwordx4 v201, s[82:83]
	s_add_i32 m0, m0, 0x2000
	s_nop 0
	global_load_lds_dwordx4 v202, s[82:83]
	s_add_u32 s82, s82, 0x10000
	s_addc_u32 s83, s83, 0

.Lat2_done_7:
	s_nop 0
	s_setprio 0
	s_mov_b32 m0, s24
	s_waitcnt lgkmcnt(0)
	s_barrier
